# ret_intra PV: V^T operands via coalesced loads + wave-local LDS staging (on top of the LDS-staged QK)
# baseline (speedup 1.0000x reference)
.LBB0_450:
	s_andn2_saveexec_b64 s[4:5], s[70:71]
	v_cvt_f32_u32_e32 v20, v38
	v_mul_f32_e32 v20, v23, v20
	v_exp_f32_e32 v37, v20
	s_or_b64 exec, exec, s[4:5]
	v_mul_f32_e32 v8, v8, v28
	v_mul_f32_e32 v9, v9, v29
	v_mul_f32_e32 v6, v6, v26
	v_mul_f32_e32 v7, v7, v27
	v_mul_f32_e32 v4, v4, v24
	v_mul_f32_e32 v5, v5, v25
	v_mul_f32_e32 v2, v2, v19
	v_mul_f32_e32 v3, v3, v22
	v_mul_f32_e32 v16, v16, v36
	v_mul_f32_e32 v14, v14, v34
	v_mul_f32_e32 v15, v15, v35
	v_mul_f32_e32 v12, v12, v32
	v_mul_f32_e32 v13, v13, v33
	v_mul_f32_e32 v10, v10, v30
	v_mul_f32_e32 v11, v11, v31
	v_mul_f32_e32 v17, v17, v37
	v_cvt_pk_bf16_f32 v2, v2, v3
	v_cvt_pk_bf16_f32 v3, v4, v5
	v_cvt_pk_bf16_f32 v4, v6, v7
	v_cvt_pk_bf16_f32 v5, v8, v9
	v_or_b32_e32 v75, v0, v190
	s_barrier
	v_cvt_pk_bf16_f32 v6, v10, v11
	v_cvt_pk_bf16_f32 v7, v12, v13
	v_cvt_pk_bf16_f32 v8, v14, v15
	v_cvt_pk_bf16_f32 v9, v16, v17
	ds_write_b128 v191, v[2:5]
	ds_write_b128 v191, v[6:9] offset:1024
	v_or_b32_e32 v2, v75, v71
	v_lshlrev_b32_e32 v34, 14, v2
	v_mov_b32_e32 v35, v1
	v_ashrrev_i32_e32 v19, 31, v18
	v_lshl_add_u64 v[2:3], s[62:63], 0, v[34:35]
	v_lshlrev_b64 v[36:37], 1, v[18:19]
	v_lshl_add_u64 v[2:3], v[2:3], 0, v[36:37]
	v_lshl_add_u64 v[36:37], v[68:69], 0, v[36:37]
	v_lshl_add_u64 v[156:157], v[36:37], 0, v[34:35]
	s_mov_b32 s4, 0x80000
	v_mov_b32_e32 v77, v1
	v_add_co_u32_e64 v38, s[4:5], s4, v156
	v_lshl_add_u64 v[32:33], v[2:3], 0, v[76:77]
	s_nop 0
	v_addc_co_u32_e64 v39, s[4:5], 0, v157, s[4:5]
	s_waitcnt lgkmcnt(0)
	s_barrier
	ds_read_b128 v[108:111], v181
	ds_read_b128 v[112:115], v181 offset:1024
	ds_read_b128 v[116:119], v181 offset:2048
	ds_read_b128 v[120:123], v181 offset:3072
	ds_read_b128 v[124:127], v181 offset:4096
	ds_read_b128 v[128:131], v181 offset:5120
	ds_read_b128 v[132:135], v181 offset:6144
	ds_read_b128 v[136:139], v181 offset:7168
	v_lshlrev_b32_e32 v245, 3, v241
	v_sub_u32_e32 v245, v245, v243
	v_lshlrev_b32_e32 v245, 14, v245
	v_lshlrev_b32_e32 v246, 4, v242
	v_lshlrev_b32_e32 v247, 3, v244
	v_sub_u32_e32 v246, v246, v247
	v_add_u32_e32 v246, v245, v246
	v_ashrrev_i32_e32 v247, 31, v246
	v_lshl_add_u64 v[228:229], v[156:157], 0, v[246:247]
	s_mov_b32 s4, 0x4000
	s_mov_b32 s5, 0
	s_mov_b32 s10, 0x64000
	s_mov_b32 s11, 0
	v_lshlrev_b32_e32 v245, 3, v244
	v_sub_u32_e32 v239, v238, v245
	global_load_dwordx4 v[80:83], v[228:229], off
	v_lshl_add_u64 v[228:229], v[228:229], 0, s[4:5]
	global_load_dwordx4 v[84:87], v[228:229], off
	v_lshl_add_u64 v[228:229], v[228:229], 0, s[4:5]
	global_load_dwordx4 v[88:91], v[228:229], off
	v_lshl_add_u64 v[228:229], v[228:229], 0, s[4:5]
	global_load_dwordx4 v[92:95], v[228:229], off
	v_lshl_add_u64 v[228:229], v[228:229], 0, s[4:5]
	global_load_dwordx4 v[96:99], v[228:229], off
	v_lshl_add_u64 v[228:229], v[228:229], 0, s[4:5]
	global_load_dwordx4 v[100:103], v[228:229], off
	v_lshl_add_u64 v[228:229], v[228:229], 0, s[4:5]
	global_load_dwordx4 v[104:107], v[228:229], off
	v_lshl_add_u64 v[228:229], v[228:229], 0, s[4:5]
	global_load_dwordx4 v[140:143], v[228:229], off
	v_lshl_add_u64 v[228:229], v[228:229], 0, s[10:11]
	global_load_dwordx4 v[144:147], v[228:229], off
	v_lshl_add_u64 v[228:229], v[228:229], 0, s[4:5]
	global_load_dwordx4 v[148:151], v[228:229], off
	v_lshl_add_u64 v[228:229], v[228:229], 0, s[4:5]
	global_load_dwordx4 v[152:155], v[228:229], off
	v_lshl_add_u64 v[228:229], v[228:229], 0, s[4:5]
	global_load_dwordx4 v[156:159], v[228:229], off
	v_lshl_add_u64 v[228:229], v[228:229], 0, s[4:5]
	global_load_dwordx4 v[160:163], v[228:229], off
	v_lshl_add_u64 v[228:229], v[228:229], 0, s[4:5]
	global_load_dwordx4 v[164:167], v[228:229], off
	v_lshl_add_u64 v[228:229], v[228:229], 0, s[4:5]
	global_load_dwordx4 v[168:171], v[228:229], off
	v_lshl_add_u64 v[228:229], v[228:229], 0, s[4:5]
	global_load_dwordx4 v[172:175], v[228:229], off
	v_lshl_add_u64 v[228:229], v[228:229], 0, s[10:11]
	s_waitcnt vmcnt(15)
	ds_write2_b64 v236, v[80:81], v[82:83] offset0:0 offset1:1
	s_waitcnt vmcnt(14)
	ds_write2_b64 v236, v[84:85], v[86:87] offset0:33 offset1:34
	s_waitcnt vmcnt(13)
	ds_write2_b64 v236, v[88:89], v[90:91] offset0:66 offset1:67
	s_waitcnt vmcnt(12)
	ds_write2_b64 v236, v[92:93], v[94:95] offset0:99 offset1:100
	s_waitcnt vmcnt(11)
	ds_write2_b64 v236, v[96:97], v[98:99] offset0:132 offset1:133
	s_waitcnt vmcnt(10)
	ds_write2_b64 v236, v[100:101], v[102:103] offset0:165 offset1:166
	s_waitcnt vmcnt(9)
	ds_write2_b64 v236, v[104:105], v[106:107] offset0:198 offset1:199
	s_waitcnt vmcnt(8)
	ds_write2_b64 v236, v[140:141], v[142:143] offset0:231 offset1:232
	s_waitcnt lgkmcnt(0)
	ds_read2_b64 v[80:83], v239 offset0:0 offset1:2
	ds_read2_b64 v[84:87], v239 offset0:4 offset1:6
	ds_read2_b64 v[88:91], v239 offset0:8 offset1:10
	ds_read2_b64 v[92:95], v239 offset0:12 offset1:14
	ds_read2_b64 v[96:99], v239 offset0:16 offset1:18
	ds_read2_b64 v[100:103], v239 offset0:20 offset1:22
	ds_read2_b64 v[104:107], v239 offset0:24 offset1:26
	ds_read2_b64 v[140:143], v239 offset0:28 offset1:30
	s_waitcnt lgkmcnt(7)
	v_mfma_f32_32x32x16_bf16 v[50:65], v[80:83], v[108:111], 0
	s_waitcnt lgkmcnt(6)
	v_mfma_f32_32x32x16_bf16 v[50:65], v[84:87], v[112:115], v[50:65]
	s_waitcnt lgkmcnt(5)
	v_mfma_f32_32x32x16_bf16 v[50:65], v[88:91], v[116:119], v[50:65]
	s_waitcnt lgkmcnt(4)
	v_mfma_f32_32x32x16_bf16 v[50:65], v[92:95], v[120:123], v[50:65]
	s_waitcnt lgkmcnt(3)
	v_mfma_f32_32x32x16_bf16 v[50:65], v[96:99], v[124:127], v[50:65]
	s_waitcnt lgkmcnt(2)
	v_mfma_f32_32x32x16_bf16 v[50:65], v[100:103], v[128:131], v[50:65]
	s_waitcnt lgkmcnt(1)
	v_mfma_f32_32x32x16_bf16 v[50:65], v[104:107], v[132:135], v[50:65]
	s_waitcnt lgkmcnt(0)
	v_mfma_f32_32x32x16_bf16 v[50:65], v[140:143], v[136:139], v[50:65]
	global_load_dwordx4 v[80:83], v[228:229], off
	v_lshl_add_u64 v[228:229], v[228:229], 0, s[4:5]
	global_load_dwordx4 v[84:87], v[228:229], off
	v_lshl_add_u64 v[228:229], v[228:229], 0, s[4:5]
	global_load_dwordx4 v[88:91], v[228:229], off
	v_lshl_add_u64 v[228:229], v[228:229], 0, s[4:5]
	global_load_dwordx4 v[92:95], v[228:229], off
	v_lshl_add_u64 v[228:229], v[228:229], 0, s[4:5]
	global_load_dwordx4 v[96:99], v[228:229], off
	v_lshl_add_u64 v[228:229], v[228:229], 0, s[4:5]
	global_load_dwordx4 v[100:103], v[228:229], off
	v_lshl_add_u64 v[228:229], v[228:229], 0, s[4:5]
	global_load_dwordx4 v[104:107], v[228:229], off
	v_lshl_add_u64 v[228:229], v[228:229], 0, s[4:5]
	global_load_dwordx4 v[140:143], v[228:229], off
	v_lshl_add_u64 v[228:229], v[228:229], 0, s[10:11]
	s_waitcnt vmcnt(15)
	ds_write2_b64 v236, v[144:145], v[146:147] offset0:0 offset1:1
	s_waitcnt vmcnt(14)
	ds_write2_b64 v236, v[148:149], v[150:151] offset0:33 offset1:34
	s_waitcnt vmcnt(13)
	ds_write2_b64 v236, v[152:153], v[154:155] offset0:66 offset1:67
	s_waitcnt vmcnt(12)
	ds_write2_b64 v236, v[156:157], v[158:159] offset0:99 offset1:100
	s_waitcnt vmcnt(11)
	ds_write2_b64 v236, v[160:161], v[162:163] offset0:132 offset1:133
	s_waitcnt vmcnt(10)
	ds_write2_b64 v236, v[164:165], v[166:167] offset0:165 offset1:166
	s_waitcnt vmcnt(9)
	ds_write2_b64 v236, v[168:169], v[170:171] offset0:198 offset1:199
	s_waitcnt vmcnt(8)
	ds_write2_b64 v236, v[172:173], v[174:175] offset0:231 offset1:232
	s_waitcnt lgkmcnt(0)
	ds_read2_b64 v[144:147], v239 offset0:0 offset1:2
	ds_read2_b64 v[148:151], v239 offset0:4 offset1:6
	ds_read2_b64 v[152:155], v239 offset0:8 offset1:10
	ds_read2_b64 v[156:159], v239 offset0:12 offset1:14
	ds_read2_b64 v[160:163], v239 offset0:16 offset1:18
	ds_read2_b64 v[164:167], v239 offset0:20 offset1:22
	ds_read2_b64 v[168:171], v239 offset0:24 offset1:26
	ds_read2_b64 v[172:175], v239 offset0:28 offset1:30
	s_waitcnt lgkmcnt(7)
	v_mfma_f32_32x32x16_bf16 v[34:49], v[144:147], v[108:111], 0
	s_waitcnt lgkmcnt(6)
	v_mfma_f32_32x32x16_bf16 v[34:49], v[148:151], v[112:115], v[34:49]
	s_waitcnt lgkmcnt(5)
	v_mfma_f32_32x32x16_bf16 v[34:49], v[152:155], v[116:119], v[34:49]
	s_waitcnt lgkmcnt(4)
	v_mfma_f32_32x32x16_bf16 v[34:49], v[156:159], v[120:123], v[34:49]
	s_waitcnt lgkmcnt(3)
	v_mfma_f32_32x32x16_bf16 v[34:49], v[160:163], v[124:127], v[34:49]
	s_waitcnt lgkmcnt(2)
	v_mfma_f32_32x32x16_bf16 v[34:49], v[164:167], v[128:131], v[34:49]
	s_waitcnt lgkmcnt(1)
	v_mfma_f32_32x32x16_bf16 v[34:49], v[168:171], v[132:135], v[34:49]
	s_waitcnt lgkmcnt(0)
	v_mfma_f32_32x32x16_bf16 v[34:49], v[172:175], v[136:139], v[34:49]
	global_load_dwordx4 v[144:147], v[228:229], off
	v_lshl_add_u64 v[228:229], v[228:229], 0, s[4:5]
	global_load_dwordx4 v[148:151], v[228:229], off
	v_lshl_add_u64 v[228:229], v[228:229], 0, s[4:5]
	global_load_dwordx4 v[152:155], v[228:229], off
	v_lshl_add_u64 v[228:229], v[228:229], 0, s[4:5]
	global_load_dwordx4 v[156:159], v[228:229], off
	v_lshl_add_u64 v[228:229], v[228:229], 0, s[4:5]
	global_load_dwordx4 v[160:163], v[228:229], off
	v_lshl_add_u64 v[228:229], v[228:229], 0, s[4:5]
	global_load_dwordx4 v[164:167], v[228:229], off
	v_lshl_add_u64 v[228:229], v[228:229], 0, s[4:5]
	global_load_dwordx4 v[168:171], v[228:229], off
	v_lshl_add_u64 v[228:229], v[228:229], 0, s[4:5]
	global_load_dwordx4 v[172:175], v[228:229], off
	s_waitcnt vmcnt(15)
	ds_write2_b64 v236, v[80:81], v[82:83] offset0:0 offset1:1
	s_waitcnt vmcnt(14)
	ds_write2_b64 v236, v[84:85], v[86:87] offset0:33 offset1:34
	s_waitcnt vmcnt(13)
	ds_write2_b64 v236, v[88:89], v[90:91] offset0:66 offset1:67
	s_waitcnt vmcnt(12)
	ds_write2_b64 v236, v[92:93], v[94:95] offset0:99 offset1:100
	s_waitcnt vmcnt(11)
	ds_write2_b64 v236, v[96:97], v[98:99] offset0:132 offset1:133
	s_waitcnt vmcnt(10)
	ds_write2_b64 v236, v[100:101], v[102:103] offset0:165 offset1:166
	s_waitcnt vmcnt(9)
	ds_write2_b64 v236, v[104:105], v[106:107] offset0:198 offset1:199
	s_waitcnt vmcnt(8)
	ds_write2_b64 v236, v[140:141], v[142:143] offset0:231 offset1:232
	s_waitcnt lgkmcnt(0)
	ds_read2_b64 v[80:83], v239 offset0:0 offset1:2
	ds_read2_b64 v[84:87], v239 offset0:4 offset1:6
	ds_read2_b64 v[88:91], v239 offset0:8 offset1:10
	ds_read2_b64 v[92:95], v239 offset0:12 offset1:14
	ds_read2_b64 v[96:99], v239 offset0:16 offset1:18
	ds_read2_b64 v[100:103], v239 offset0:20 offset1:22
	ds_read2_b64 v[104:107], v239 offset0:24 offset1:26
	ds_read2_b64 v[140:143], v239 offset0:28 offset1:30
	s_waitcnt lgkmcnt(7)
	v_mfma_f32_32x32x16_bf16 v[18:33], v[80:83], v[108:111], 0
	s_waitcnt lgkmcnt(6)
	v_mfma_f32_32x32x16_bf16 v[18:33], v[84:87], v[112:115], v[18:33]
	s_waitcnt lgkmcnt(5)
	v_mfma_f32_32x32x16_bf16 v[18:33], v[88:91], v[116:119], v[18:33]
	s_waitcnt lgkmcnt(4)
	v_mfma_f32_32x32x16_bf16 v[18:33], v[92:95], v[120:123], v[18:33]
	s_waitcnt lgkmcnt(3)
	v_mfma_f32_32x32x16_bf16 v[18:33], v[96:99], v[124:127], v[18:33]
	s_waitcnt lgkmcnt(2)
	v_mfma_f32_32x32x16_bf16 v[18:33], v[100:103], v[128:131], v[18:33]
	s_waitcnt lgkmcnt(1)
	v_mfma_f32_32x32x16_bf16 v[18:33], v[104:107], v[132:135], v[18:33]
	s_waitcnt lgkmcnt(0)
	v_mfma_f32_32x32x16_bf16 v[18:33], v[140:143], v[136:139], v[18:33]
	s_waitcnt vmcnt(7)
	ds_write2_b64 v236, v[144:145], v[146:147] offset0:0 offset1:1
	s_waitcnt vmcnt(6)
	ds_write2_b64 v236, v[148:149], v[150:151] offset0:33 offset1:34
	s_waitcnt vmcnt(5)
	ds_write2_b64 v236, v[152:153], v[154:155] offset0:66 offset1:67
	s_waitcnt vmcnt(4)
	ds_write2_b64 v236, v[156:157], v[158:159] offset0:99 offset1:100
	s_waitcnt vmcnt(3)
	ds_write2_b64 v236, v[160:161], v[162:163] offset0:132 offset1:133
	s_waitcnt vmcnt(2)
	ds_write2_b64 v236, v[164:165], v[166:167] offset0:165 offset1:166
	s_waitcnt vmcnt(1)
	ds_write2_b64 v236, v[168:169], v[170:171] offset0:198 offset1:199
	s_waitcnt vmcnt(0)
	ds_write2_b64 v236, v[172:173], v[174:175] offset0:231 offset1:232
	s_waitcnt lgkmcnt(0)
	ds_read2_b64 v[144:147], v239 offset0:0 offset1:2
	ds_read2_b64 v[148:151], v239 offset0:4 offset1:6
	ds_read2_b64 v[152:155], v239 offset0:8 offset1:10
	ds_read2_b64 v[156:159], v239 offset0:12 offset1:14
	ds_read2_b64 v[160:163], v239 offset0:16 offset1:18
	ds_read2_b64 v[164:167], v239 offset0:20 offset1:22
	ds_read2_b64 v[168:171], v239 offset0:24 offset1:26
	ds_read2_b64 v[172:175], v239 offset0:28 offset1:30
	s_waitcnt lgkmcnt(7)
	v_mfma_f32_32x32x16_bf16 v[2:17], v[144:147], v[108:111], 0
	s_waitcnt lgkmcnt(6)
	v_mfma_f32_32x32x16_bf16 v[2:17], v[148:151], v[112:115], v[2:17]
	s_waitcnt lgkmcnt(5)
	v_mfma_f32_32x32x16_bf16 v[2:17], v[152:155], v[116:119], v[2:17]
	s_waitcnt lgkmcnt(4)
	v_mfma_f32_32x32x16_bf16 v[2:17], v[156:159], v[120:123], v[2:17]
	s_waitcnt lgkmcnt(3)
	v_mfma_f32_32x32x16_bf16 v[2:17], v[160:163], v[124:127], v[2:17]
	s_waitcnt lgkmcnt(2)
	v_mfma_f32_32x32x16_bf16 v[2:17], v[164:167], v[128:131], v[2:17]
	s_waitcnt lgkmcnt(1)
	v_mfma_f32_32x32x16_bf16 v[2:17], v[168:171], v[132:135], v[2:17]
	s_waitcnt lgkmcnt(0)
	v_mfma_f32_32x32x16_bf16 v[2:17], v[172:175], v[136:139], v[2:17]
	v_or_b32_e32 v0, v70, v0
	v_or_b32_e32 v80, v0, v78
	v_mov_b32_e32 v81, v79
	v_lshlrev_b64 v[80:81], 1, v[80:81]
	v_bfe_u32 v112, v189, 5, 1
	v_lshlrev_b32_e32 v112, 3, v112
	v_mov_b32_e32 v113, 0
	v_lshl_add_u64 v[80:81], v[80:81], 0, v[112:113]
	v_lshl_add_u64 v[82:83], s[64:65], 0, v[80:81]
	v_lshl_add_u64 v[84:85], s[66:67], 0, v[80:81]
	v_lshl_add_u64 v[80:81], s[68:69], 0, v[80:81]
	global_load_dwordx4 v[114:117], v[82:83], off
	global_load_dwordx4 v[122:125], v[82:83], off offset:32
	global_load_dwordx4 v[130:133], v[82:83], off offset:64
	global_load_dwordx4 v[138:141], v[82:83], off offset:96
	global_load_dwordx4 v[146:149], v[82:83], off offset:128
	global_load_dwordx4 v[154:157], v[82:83], off offset:160
	global_load_dwordx4 v[162:165], v[82:83], off offset:192
	global_load_dwordx4 v[170:173], v[82:83], off offset:224
	global_load_dwordx4 v[118:121], v[84:85], off
	global_load_dwordx4 v[126:129], v[84:85], off offset:32
	global_load_dwordx4 v[134:137], v[84:85], off offset:64
	global_load_dwordx4 v[142:145], v[84:85], off offset:96
	global_load_dwordx4 v[150:153], v[84:85], off offset:128
	global_load_dwordx4 v[158:161], v[84:85], off offset:160
	global_load_dwordx4 v[166:169], v[84:85], off offset:192
	global_load_dwordx4 v[174:177], v[84:85], off offset:224
	global_load_dwordx4 v[108:111], v[80:81], off
	global_load_dwordx4 v[104:107], v[80:81], off offset:32
	global_load_dwordx4 v[100:103], v[80:81], off offset:64
	global_load_dwordx4 v[96:99], v[80:81], off offset:96
	global_load_dwordx4 v[92:95], v[80:81], off offset:128
	global_load_dwordx4 v[88:91], v[80:81], off offset:160
	global_load_dwordx4 v[84:87], v[80:81], off offset:192
	global_load_dwordx4 v[80:83], v[80:81], off offset:224
	s_waitcnt vmcnt(0)
	v_permlane32_swap_b32_e32 v114, v116
	v_permlane32_swap_b32_e32 v115, v117
	v_permlane32_swap_b32_e32 v122, v124
	v_permlane32_swap_b32_e32 v123, v125
	v_permlane32_swap_b32_e32 v130, v132
	v_permlane32_swap_b32_e32 v131, v133
	v_permlane32_swap_b32_e32 v138, v140
	v_permlane32_swap_b32_e32 v139, v141
	v_permlane32_swap_b32_e32 v146, v148
	v_permlane32_swap_b32_e32 v147, v149
	v_permlane32_swap_b32_e32 v154, v156
	v_permlane32_swap_b32_e32 v155, v157
	v_permlane32_swap_b32_e32 v162, v164
	v_permlane32_swap_b32_e32 v163, v165
	v_permlane32_swap_b32_e32 v170, v172
	v_permlane32_swap_b32_e32 v171, v173
	v_permlane32_swap_b32_e32 v118, v120
	v_permlane32_swap_b32_e32 v119, v121
	v_permlane32_swap_b32_e32 v126, v128
	v_permlane32_swap_b32_e32 v127, v129
	v_permlane32_swap_b32_e32 v134, v136
	v_permlane32_swap_b32_e32 v135, v137
	v_permlane32_swap_b32_e32 v142, v144
	v_permlane32_swap_b32_e32 v143, v145
	v_permlane32_swap_b32_e32 v150, v152
	v_permlane32_swap_b32_e32 v151, v153
	v_permlane32_swap_b32_e32 v158, v160
	v_permlane32_swap_b32_e32 v159, v161
	v_permlane32_swap_b32_e32 v166, v168
	v_permlane32_swap_b32_e32 v167, v169
	v_permlane32_swap_b32_e32 v174, v176
	v_permlane32_swap_b32_e32 v175, v177
	v_permlane32_swap_b32_e32 v108, v110
	v_permlane32_swap_b32_e32 v109, v111
	v_permlane32_swap_b32_e32 v104, v106
	v_permlane32_swap_b32_e32 v105, v107
	v_permlane32_swap_b32_e32 v100, v102
	v_permlane32_swap_b32_e32 v101, v103
	v_permlane32_swap_b32_e32 v96, v98
	v_permlane32_swap_b32_e32 v97, v99
	v_permlane32_swap_b32_e32 v92, v94
	v_permlane32_swap_b32_e32 v93, v95
	v_permlane32_swap_b32_e32 v88, v90
	v_permlane32_swap_b32_e32 v89, v91
	v_permlane32_swap_b32_e32 v84, v86
	v_permlane32_swap_b32_e32 v85, v87
	v_permlane32_swap_b32_e32 v80, v82
	v_permlane32_swap_b32_e32 v81, v83
	v_swap_b32 v116, v118
	v_swap_b32 v117, v119
	v_swap_b32 v124, v126
	v_swap_b32 v125, v127
	v_swap_b32 v132, v134
	v_swap_b32 v133, v135
	v_swap_b32 v140, v142
	v_swap_b32 v141, v143
	v_swap_b32 v148, v150
	v_swap_b32 v149, v151
	v_swap_b32 v156, v158
	v_swap_b32 v157, v159
	v_swap_b32 v168, v170
	v_swap_b32 v169, v171
	v_swap_b32 v108, v110
	v_swap_b32 v109, v111
	v_swap_b32 v104, v106
	v_swap_b32 v105, v107
	v_swap_b32 v100, v102
	v_swap_b32 v101, v103
	v_swap_b32 v96, v98
	v_swap_b32 v97, v99
	v_swap_b32 v92, v94
	v_swap_b32 v93, v95
	v_swap_b32 v88, v90
	v_swap_b32 v89, v91
	v_swap_b32 v84, v86
	v_swap_b32 v85, v87
	v_swap_b32 v80, v82
	v_swap_b32 v81, v83
	v_lshlrev_b32_e32 v112, 16, v114
	v_and_b32_e32 v113, 0xffff0000, v114
	s_waitcnt vmcnt(43)
	v_lshlrev_b32_e32 v178, 16, v116
	v_and_b32_e32 v179, 0xffff0000, v116
	v_pk_add_f32 v[112:113], v[112:113], v[178:179]
	v_lshlrev_b32_e32 v114, 16, v117
	v_pk_add_f32 v[112:113], v[50:51], v[112:113]
	v_lshlrev_b32_e32 v50, 16, v115
	v_and_b32_e32 v51, 0xffff0000, v115
	v_and_b32_e32 v115, 0xffff0000, v117
	v_pk_add_f32 v[50:51], v[50:51], v[114:115]
	v_add_f32_e32 v0, 0, v112
	v_pk_add_f32 v[114:115], v[52:53], v[50:51]
	v_add_f32_e32 v52, v113, v0
	v_mul_f32_e32 v0, v113, v113
	v_pk_fma_f32 v[50:51], v[112:113], v[112:113], v[0:1] op_sel_hi:[1,1,0]
	v_add_f32_e32 v0, v114, v52
	v_lshlrev_b32_e32 v52, 16, v118
	v_and_b32_e32 v53, 0xffff0000, v118
	s_waitcnt vmcnt(42)
	v_lshlrev_b32_e32 v116, 16, v120
	v_and_b32_e32 v117, 0xffff0000, v120
	v_pk_add_f32 v[52:53], v[52:53], v[116:117]
	v_pk_fma_f32 v[50:51], v[114:115], v[114:115], v[50:51]
	v_add_f32_e32 v77, v115, v0
	v_mul_f32_e32 v0, v115, v115
	v_pk_add_f32 v[116:117], v[54:55], v[52:53]
	v_lshlrev_b32_e32 v52, 16, v119
	v_and_b32_e32 v53, 0xffff0000, v119
	v_lshlrev_b32_e32 v54, 16, v121
	v_and_b32_e32 v55, 0xffff0000, v121
	v_pk_add_f32 v[50:51], v[0:1], v[50:51] op_sel_hi:[0,1]
	v_pk_add_f32 v[52:53], v[52:53], v[54:55]
	v_add_f32_e32 v0, v116, v77
	v_pk_add_f32 v[118:119], v[56:57], v[52:53]
	v_pk_fma_f32 v[50:51], v[116:117], v[116:117], v[50:51]
	v_add_f32_e32 v52, v117, v0
	v_mul_f32_e32 v0, v117, v117
	v_pk_add_f32 v[50:51], v[0:1], v[50:51] op_sel_hi:[0,1]
	v_add_f32_e32 v0, v118, v52
	v_lshlrev_b32_e32 v52, 16, v122
	v_and_b32_e32 v53, 0xffff0000, v122
	s_waitcnt vmcnt(41)
	v_lshlrev_b32_e32 v54, 16, v124
	v_and_b32_e32 v55, 0xffff0000, v124
	v_pk_add_f32 v[52:53], v[52:53], v[54:55]
	v_pk_fma_f32 v[50:51], v[118:119], v[118:119], v[50:51]
	v_add_f32_e32 v56, v119, v0
	v_mul_f32_e32 v0, v119, v119
	v_pk_add_f32 v[120:121], v[58:59], v[52:53]
	v_lshlrev_b32_e32 v52, 16, v123
	v_and_b32_e32 v53, 0xffff0000, v123
	v_lshlrev_b32_e32 v54, 16, v125
	v_and_b32_e32 v55, 0xffff0000, v125
	v_pk_add_f32 v[50:51], v[0:1], v[50:51] op_sel_hi:[0,1]
	v_pk_add_f32 v[52:53], v[52:53], v[54:55]
	v_add_f32_e32 v0, v120, v56
	v_pk_add_f32 v[122:123], v[60:61], v[52:53]
	v_pk_fma_f32 v[50:51], v[120:121], v[120:121], v[50:51]
	v_add_f32_e32 v52, v121, v0
	v_mul_f32_e32 v0, v121, v121
	v_pk_add_f32 v[50:51], v[0:1], v[50:51] op_sel_hi:[0,1]
	v_add_f32_e32 v0, v122, v52
	v_lshlrev_b32_e32 v52, 16, v126
	v_and_b32_e32 v53, 0xffff0000, v126
	s_waitcnt vmcnt(40)
	v_lshlrev_b32_e32 v54, 16, v128
	v_and_b32_e32 v55, 0xffff0000, v128
	v_pk_add_f32 v[52:53], v[52:53], v[54:55]
	v_pk_fma_f32 v[50:51], v[122:123], v[122:123], v[50:51]
	v_add_f32_e32 v56, v123, v0
	v_mul_f32_e32 v0, v123, v123
	v_pk_add_f32 v[124:125], v[62:63], v[52:53]
	v_lshlrev_b32_e32 v52, 16, v127
	v_and_b32_e32 v53, 0xffff0000, v127
	v_lshlrev_b32_e32 v54, 16, v129
	v_and_b32_e32 v55, 0xffff0000, v129
	v_pk_add_f32 v[50:51], v[0:1], v[50:51] op_sel_hi:[0,1]
	v_pk_add_f32 v[52:53], v[52:53], v[54:55]
	v_add_f32_e32 v0, v124, v56
	v_pk_add_f32 v[126:127], v[64:65], v[52:53]
	v_pk_fma_f32 v[50:51], v[124:125], v[124:125], v[50:51]
	v_add_f32_e32 v52, v125, v0
	v_mul_f32_e32 v0, v125, v125
	v_pk_add_f32 v[50:51], v[0:1], v[50:51] op_sel_hi:[0,1]
	v_add_f32_e32 v0, v126, v52
	s_waitcnt vmcnt(35)
	v_lshlrev_b32_e32 v52, 16, v130
	v_and_b32_e32 v53, 0xffff0000, v130
	s_waitcnt vmcnt(31)
	v_lshlrev_b32_e32 v54, 16, v132
	v_and_b32_e32 v55, 0xffff0000, v132
	v_pk_add_f32 v[52:53], v[52:53], v[54:55]
	v_pk_fma_f32 v[50:51], v[126:127], v[126:127], v[50:51]
	v_add_f32_e32 v56, v127, v0
	v_mul_f32_e32 v0, v127, v127
	v_pk_add_f32 v[128:129], v[34:35], v[52:53]
	v_lshlrev_b32_e32 v34, 16, v131
	v_and_b32_e32 v35, 0xffff0000, v131
	v_lshlrev_b32_e32 v52, 16, v133
	v_and_b32_e32 v53, 0xffff0000, v133
	v_pk_add_f32 v[50:51], v[0:1], v[50:51] op_sel_hi:[0,1]
	v_pk_add_f32 v[34:35], v[34:35], v[52:53]
	v_add_f32_e32 v0, v128, v56
	v_pk_add_f32 v[130:131], v[36:37], v[34:35]
	v_pk_fma_f32 v[34:35], v[128:129], v[128:129], v[50:51]
	v_add_f32_e32 v36, v129, v0
	v_mul_f32_e32 v0, v129, v129
	v_pk_add_f32 v[34:35], v[0:1], v[34:35] op_sel_hi:[0,1]
	v_add_f32_e32 v0, v130, v36
	v_lshlrev_b32_e32 v36, 16, v134
	v_and_b32_e32 v37, 0xffff0000, v134
	s_waitcnt vmcnt(30)
	v_lshlrev_b32_e32 v50, 16, v136
	v_and_b32_e32 v51, 0xffff0000, v136
	v_pk_add_f32 v[36:37], v[36:37], v[50:51]
	v_pk_fma_f32 v[34:35], v[130:131], v[130:131], v[34:35]
	v_add_f32_e32 v52, v131, v0
	v_mul_f32_e32 v0, v131, v131
	v_pk_add_f32 v[132:133], v[38:39], v[36:37]
	v_lshlrev_b32_e32 v36, 16, v135
	v_and_b32_e32 v37, 0xffff0000, v135
	v_lshlrev_b32_e32 v38, 16, v137
	v_and_b32_e32 v39, 0xffff0000, v137
	v_pk_add_f32 v[34:35], v[0:1], v[34:35] op_sel_hi:[0,1]
	v_pk_add_f32 v[36:37], v[36:37], v[38:39]
	v_add_f32_e32 v0, v132, v52
	v_pk_add_f32 v[134:135], v[40:41], v[36:37]
	v_pk_fma_f32 v[34:35], v[132:133], v[132:133], v[34:35]
	v_add_f32_e32 v36, v133, v0
	v_mul_f32_e32 v0, v133, v133
	v_pk_add_f32 v[34:35], v[0:1], v[34:35] op_sel_hi:[0,1]
	v_add_f32_e32 v0, v134, v36
	v_lshlrev_b32_e32 v36, 16, v138
	v_and_b32_e32 v37, 0xffff0000, v138
	s_waitcnt vmcnt(29)
	v_lshlrev_b32_e32 v38, 16, v140
	v_and_b32_e32 v39, 0xffff0000, v140
	v_pk_add_f32 v[36:37], v[36:37], v[38:39]
	v_pk_fma_f32 v[34:35], v[134:135], v[134:135], v[34:35]
	v_add_f32_e32 v40, v135, v0
	v_mul_f32_e32 v0, v135, v135
	v_pk_add_f32 v[136:137], v[42:43], v[36:37]
	v_lshlrev_b32_e32 v36, 16, v139
	v_and_b32_e32 v37, 0xffff0000, v139
	v_lshlrev_b32_e32 v38, 16, v141
	v_and_b32_e32 v39, 0xffff0000, v141
	v_pk_add_f32 v[34:35], v[0:1], v[34:35] op_sel_hi:[0,1]
	v_pk_add_f32 v[36:37], v[36:37], v[38:39]
	v_add_f32_e32 v0, v136, v40
	v_pk_add_f32 v[138:139], v[44:45], v[36:37]
	v_pk_fma_f32 v[34:35], v[136:137], v[136:137], v[34:35]
	v_add_f32_e32 v36, v137, v0
	v_mul_f32_e32 v0, v137, v137
	v_pk_add_f32 v[34:35], v[0:1], v[34:35] op_sel_hi:[0,1]
	v_add_f32_e32 v0, v138, v36
	v_lshlrev_b32_e32 v36, 16, v142
	v_and_b32_e32 v37, 0xffff0000, v142
	s_waitcnt vmcnt(28)
	v_lshlrev_b32_e32 v38, 16, v144
	v_and_b32_e32 v39, 0xffff0000, v144
	v_pk_add_f32 v[36:37], v[36:37], v[38:39]
	v_pk_fma_f32 v[34:35], v[138:139], v[138:139], v[34:35]
	v_add_f32_e32 v40, v139, v0
	v_mul_f32_e32 v0, v139, v139
	v_pk_add_f32 v[140:141], v[46:47], v[36:37]
	v_lshlrev_b32_e32 v36, 16, v143
	v_and_b32_e32 v37, 0xffff0000, v143
	v_lshlrev_b32_e32 v38, 16, v145
	v_and_b32_e32 v39, 0xffff0000, v145
	v_pk_add_f32 v[34:35], v[0:1], v[34:35] op_sel_hi:[0,1]
	v_pk_add_f32 v[36:37], v[36:37], v[38:39]
	v_add_f32_e32 v0, v140, v40
	v_pk_add_f32 v[142:143], v[48:49], v[36:37]
	v_pk_fma_f32 v[34:35], v[140:141], v[140:141], v[34:35]
	v_add_f32_e32 v36, v141, v0
	v_mul_f32_e32 v0, v141, v141
	v_pk_add_f32 v[34:35], v[0:1], v[34:35] op_sel_hi:[0,1]
	v_add_f32_e32 v0, v142, v36
	s_waitcnt vmcnt(23)
	v_lshlrev_b32_e32 v36, 16, v146
	v_and_b32_e32 v37, 0xffff0000, v146
	s_waitcnt vmcnt(19)
	v_lshlrev_b32_e32 v38, 16, v148
	v_and_b32_e32 v39, 0xffff0000, v148
	v_pk_add_f32 v[36:37], v[36:37], v[38:39]
	v_pk_fma_f32 v[34:35], v[142:143], v[142:143], v[34:35]
	v_add_f32_e32 v40, v143, v0
	v_mul_f32_e32 v0, v143, v143
	v_pk_add_f32 v[144:145], v[18:19], v[36:37]
	v_lshlrev_b32_e32 v18, 16, v147
	v_and_b32_e32 v19, 0xffff0000, v147
	v_lshlrev_b32_e32 v36, 16, v149
	v_and_b32_e32 v37, 0xffff0000, v149
	v_pk_add_f32 v[34:35], v[0:1], v[34:35] op_sel_hi:[0,1]
	v_pk_add_f32 v[18:19], v[18:19], v[36:37]
	v_add_f32_e32 v0, v144, v40
	v_pk_add_f32 v[146:147], v[20:21], v[18:19]
	v_pk_fma_f32 v[18:19], v[144:145], v[144:145], v[34:35]
	v_add_f32_e32 v20, v145, v0
	v_mul_f32_e32 v0, v145, v145
	v_pk_add_f32 v[18:19], v[0:1], v[18:19] op_sel_hi:[0,1]
	v_add_f32_e32 v0, v146, v20
	v_lshlrev_b32_e32 v20, 16, v150
	v_and_b32_e32 v21, 0xffff0000, v150
	s_waitcnt vmcnt(18)
	v_lshlrev_b32_e32 v34, 16, v152
	v_and_b32_e32 v35, 0xffff0000, v152
	v_pk_add_f32 v[20:21], v[20:21], v[34:35]
	v_pk_fma_f32 v[18:19], v[146:147], v[146:147], v[18:19]
	v_add_f32_e32 v36, v147, v0
	v_mul_f32_e32 v0, v147, v147
	v_pk_add_f32 v[148:149], v[22:23], v[20:21]
	v_lshlrev_b32_e32 v20, 16, v151
	v_and_b32_e32 v21, 0xffff0000, v151
	v_lshlrev_b32_e32 v22, 16, v153
	v_and_b32_e32 v23, 0xffff0000, v153
	v_pk_add_f32 v[18:19], v[0:1], v[18:19] op_sel_hi:[0,1]
	v_pk_add_f32 v[20:21], v[20:21], v[22:23]
	v_add_f32_e32 v0, v148, v36
	v_pk_add_f32 v[150:151], v[24:25], v[20:21]
	v_pk_fma_f32 v[18:19], v[148:149], v[148:149], v[18:19]
	v_add_f32_e32 v20, v149, v0
	v_mul_f32_e32 v0, v149, v149
	v_pk_add_f32 v[18:19], v[0:1], v[18:19] op_sel_hi:[0,1]
	v_add_f32_e32 v0, v150, v20
	v_lshlrev_b32_e32 v20, 16, v154
	v_and_b32_e32 v21, 0xffff0000, v154
	s_waitcnt vmcnt(17)
	v_lshlrev_b32_e32 v22, 16, v156
	v_and_b32_e32 v23, 0xffff0000, v156
	v_pk_add_f32 v[20:21], v[20:21], v[22:23]
	v_pk_fma_f32 v[18:19], v[150:151], v[150:151], v[18:19]
	v_add_f32_e32 v24, v151, v0
	v_mul_f32_e32 v0, v151, v151
	v_pk_add_f32 v[152:153], v[26:27], v[20:21]
	v_lshlrev_b32_e32 v20, 16, v155
	v_and_b32_e32 v21, 0xffff0000, v155
	v_lshlrev_b32_e32 v22, 16, v157
	v_and_b32_e32 v23, 0xffff0000, v157
	v_pk_add_f32 v[18:19], v[0:1], v[18:19] op_sel_hi:[0,1]
	v_pk_add_f32 v[20:21], v[20:21], v[22:23]
	v_add_f32_e32 v0, v152, v24
	v_pk_add_f32 v[154:155], v[28:29], v[20:21]
	v_pk_fma_f32 v[18:19], v[152:153], v[152:153], v[18:19]
	v_add_f32_e32 v20, v153, v0
	v_mul_f32_e32 v0, v153, v153
	v_pk_add_f32 v[18:19], v[0:1], v[18:19] op_sel_hi:[0,1]
	v_add_f32_e32 v0, v154, v20
	v_lshlrev_b32_e32 v20, 16, v158
	v_and_b32_e32 v21, 0xffff0000, v158
	s_waitcnt vmcnt(16)
	v_lshlrev_b32_e32 v22, 16, v160
	v_and_b32_e32 v23, 0xffff0000, v160
	v_pk_add_f32 v[20:21], v[20:21], v[22:23]
	v_pk_fma_f32 v[18:19], v[154:155], v[154:155], v[18:19]
	v_add_f32_e32 v24, v155, v0
	v_mul_f32_e32 v0, v155, v155
	v_pk_add_f32 v[156:157], v[30:31], v[20:21]
	v_lshlrev_b32_e32 v20, 16, v159
	v_and_b32_e32 v21, 0xffff0000, v159
	v_lshlrev_b32_e32 v22, 16, v161
	v_and_b32_e32 v23, 0xffff0000, v161
	v_pk_add_f32 v[18:19], v[0:1], v[18:19] op_sel_hi:[0,1]
	v_pk_add_f32 v[20:21], v[20:21], v[22:23]
	v_add_f32_e32 v0, v156, v24
	v_pk_add_f32 v[158:159], v[32:33], v[20:21]
	v_pk_fma_f32 v[18:19], v[156:157], v[156:157], v[18:19]
	v_add_f32_e32 v20, v157, v0
	v_mul_f32_e32 v0, v157, v157
	v_pk_add_f32 v[18:19], v[0:1], v[18:19] op_sel_hi:[0,1]
	v_add_f32_e32 v0, v158, v20
	s_waitcnt vmcnt(11)
	v_lshlrev_b32_e32 v20, 16, v162
	v_and_b32_e32 v21, 0xffff0000, v162
	s_waitcnt vmcnt(7)
	v_lshlrev_b32_e32 v22, 16, v166
	v_and_b32_e32 v23, 0xffff0000, v166
	v_pk_add_f32 v[20:21], v[20:21], v[22:23]
	v_pk_fma_f32 v[18:19], v[158:159], v[158:159], v[18:19]
	v_add_f32_e32 v24, v159, v0
	v_mul_f32_e32 v0, v159, v159
	v_pk_add_f32 v[160:161], v[2:3], v[20:21]
	v_lshlrev_b32_e32 v2, 16, v163
	v_and_b32_e32 v3, 0xffff0000, v163
	v_lshlrev_b32_e32 v20, 16, v167
	v_and_b32_e32 v21, 0xffff0000, v167
	v_pk_add_f32 v[18:19], v[0:1], v[18:19] op_sel_hi:[0,1]
	v_pk_add_f32 v[2:3], v[2:3], v[20:21]
	v_add_f32_e32 v0, v160, v24
	v_pk_add_f32 v[162:163], v[4:5], v[2:3]
	v_pk_fma_f32 v[2:3], v[160:161], v[160:161], v[18:19]
	v_add_f32_e32 v4, v161, v0
	v_mul_f32_e32 v0, v161, v161
	v_pk_add_f32 v[2:3], v[0:1], v[2:3] op_sel_hi:[0,1]
	v_add_f32_e32 v0, v162, v4
	v_lshlrev_b32_e32 v4, 16, v164
	v_and_b32_e32 v5, 0xffff0000, v164
	s_waitcnt vmcnt(6)
	v_lshlrev_b32_e32 v18, 16, v170
	v_and_b32_e32 v19, 0xffff0000, v170
	v_pk_add_f32 v[4:5], v[4:5], v[18:19]
	v_add_f32_e32 v0, v163, v0
	v_pk_add_f32 v[166:167], v[6:7], v[4:5]
	v_lshlrev_b32_e32 v4, 16, v165
	v_and_b32_e32 v5, 0xffff0000, v165
	v_lshlrev_b32_e32 v6, 16, v171
	v_and_b32_e32 v7, 0xffff0000, v171
	v_pk_fma_f32 v[2:3], v[162:163], v[162:163], v[2:3]
	v_pk_add_f32 v[4:5], v[4:5], v[6:7]
	v_add_f32_e32 v6, v166, v0
	v_mul_f32_e32 v0, v163, v163
	v_pk_add_f32 v[164:165], v[8:9], v[4:5]
	v_mov_b32_e32 v4, v166
	v_mov_b32_e32 v5, v163
	v_pk_add_f32 v[2:3], v[0:1], v[2:3] op_sel_hi:[0,1]
	v_add_f32_e32 v0, v167, v6
	v_pk_fma_f32 v[2:3], v[4:5], v[4:5], v[2:3]
	v_add_f32_e32 v6, v164, v0
	v_mul_f32_e32 v0, v167, v167
	v_mov_b32_e32 v4, v164
	v_mov_b32_e32 v5, v167
	v_pk_add_f32 v[2:3], v[0:1], v[2:3] op_sel_hi:[0,1]
	v_pk_fma_f32 v[2:3], v[4:5], v[4:5], v[2:3]
	v_add_f32_e32 v0, v165, v6
	v_lshlrev_b32_e32 v4, 16, v168
	v_and_b32_e32 v5, 0xffff0000, v168
	s_waitcnt vmcnt(5)
	v_lshlrev_b32_e32 v6, 16, v174
	v_and_b32_e32 v7, 0xffff0000, v174
	v_pk_add_f32 v[4:5], v[4:5], v[6:7]
	v_lshlrev_b32_e32 v6, 16, v175
	v_pk_add_f32 v[170:171], v[10:11], v[4:5]
	v_lshlrev_b32_e32 v4, 16, v169
	v_and_b32_e32 v5, 0xffff0000, v169
	v_and_b32_e32 v7, 0xffff0000, v175
	v_pk_add_f32 v[4:5], v[4:5], v[6:7]
	v_add_f32_e32 v6, v170, v0
	v_mul_f32_e32 v0, v165, v165
	v_pk_add_f32 v[168:169], v[12:13], v[4:5]
	v_mov_b32_e32 v4, v170
	v_mov_b32_e32 v5, v165
	v_pk_add_f32 v[2:3], v[0:1], v[2:3] op_sel_hi:[0,1]
	v_add_f32_e32 v0, v171, v6
	v_pk_fma_f32 v[2:3], v[4:5], v[4:5], v[2:3]
	v_add_f32_e32 v6, v168, v0
	v_mul_f32_e32 v0, v171, v171
	v_mov_b32_e32 v4, v168
	v_mov_b32_e32 v5, v171
	v_pk_add_f32 v[2:3], v[0:1], v[2:3] op_sel_hi:[0,1]
	v_pk_fma_f32 v[2:3], v[4:5], v[4:5], v[2:3]
	v_add_f32_e32 v77, v169, v6
	v_lshlrev_b32_e32 v4, 16, v172
	v_and_b32_e32 v5, 0xffff0000, v172
	s_waitcnt vmcnt(4)
	v_lshlrev_b32_e32 v6, 16, v176
	v_and_b32_e32 v7, 0xffff0000, v176
	v_pk_add_f32 v[4:5], v[4:5], v[6:7]
	v_lshlrev_b32_e32 v6, 16, v177
	v_pk_add_f32 v[174:175], v[14:15], v[4:5]
	v_lshlrev_b32_e32 v4, 16, v173
	v_and_b32_e32 v5, 0xffff0000, v173
	v_and_b32_e32 v7, 0xffff0000, v177
	v_pk_add_f32 v[4:5], v[4:5], v[6:7]
	v_mul_f32_e32 v0, v169, v169
	v_pk_add_f32 v[172:173], v[16:17], v[4:5]
	v_mov_b32_e32 v4, v174
	v_mov_b32_e32 v5, v169
	v_pk_add_f32 v[2:3], v[0:1], v[2:3] op_sel_hi:[0,1]
	v_pk_fma_f32 v[2:3], v[4:5], v[4:5], v[2:3]
	v_mul_f32_e32 v0, v175, v175
	v_mov_b32_e32 v4, v172
	v_mov_b32_e32 v5, v175
	v_pk_add_f32 v[2:3], v[0:1], v[2:3] op_sel_hi:[0,1]
	v_lshlrev_b32_e32 v0, 11, v226
	v_pk_fma_f32 v[178:179], v[4:5], v[4:5], v[2:3]
	v_lshl_add_u64 v[2:3], v[72:73], 0, v[0:1]
	global_load_dwordx4 v[62:65], v[2:3], off
	global_load_dwordx4 v[58:61], v[2:3], off offset:32
	global_load_dwordx4 v[54:57], v[2:3], off offset:64
	global_load_dwordx4 v[50:53], v[2:3], off offset:96
	global_load_dwordx4 v[46:49], v[2:3], off offset:128
	global_load_dwordx4 v[42:45], v[2:3], off offset:160
	global_load_dwordx4 v[38:41], v[2:3], off offset:192
	global_load_dwordx4 v[34:37], v[2:3], off offset:224
	global_load_dwordx4 v[30:33], v[2:3], off offset:256
	global_load_dwordx4 v[26:29], v[2:3], off offset:288
	global_load_dwordx4 v[22:25], v[2:3], off offset:320
	global_load_dwordx4 v[18:21], v[2:3], off offset:352
	global_load_dwordx4 v[14:17], v[2:3], off offset:384
	global_load_dwordx4 v[10:13], v[2:3], off offset:416
	global_load_dwordx4 v[6:9], v[2:3], off offset:448
	s_nop 0
	global_load_dwordx4 v[2:5], v[2:3], off offset:480
	v_add_f32_e32 v0, v174, v77
	v_pk_mul_f32 v[176:177], v[172:173], v[172:173]
	v_add_f32_e32 v0, v175, v0
	v_add_f32_e32 v176, v172, v0
	v_pk_mov_b32 v[178:179], v[172:173], v[178:179] op_sel:[1,0]
	s_nop 0
	v_pk_add_f32 v[176:177], v[178:179], v[176:177]
	ds_bpermute_b32 v178, v192, v176
	ds_bpermute_b32 v179, v192, v177
	s_and_saveexec_b64 s[4:5], vcc
	s_cbranch_execz .LBB0_387
	s_waitcnt lgkmcnt(0)
	v_pk_add_f32 v[176:177], v[176:177], v[178:179]
	ds_write_b64 v193, v[176:177] offset:8192
	s_branch .LBB0_387
